# attention loops: LDS fragment reads software-pipelined (QK first block de-serialized, QK1/PV reads hoisted)
# speedup vs baseline: 1.0006x; 1.0006x over previous
; template <int DH, bool MOBA>
; __device__ __forceinline__ void flash_pass(LAS unsigned char* lds, const bf16_t* qrow, const bf16_t* kbase, const bf16_t* vtbase, int q0, int qblk, float sl2, unsigned sel, f32x16 (&o)[4], int tid) {
;     ...
;                 const float fb0 = fb, fb1 = fb + sl2 * 16.0f;
; #pragma unroll
;                 for (int r = 0; r < 16; ++r) s[0][r] = ((r >> 3) ? fb1 : fb0) + sl2 * (float)(r & 7);
;             }
;             const float fb2 = fb + sl2 * 32.0f, fb3 = fb + sl2 * 48.0f;
;             __builtin_amdgcn_s_setprio(1);
; #pragma unroll
;             for (int g0 = 0; g0 < NQK; g0 += 4) {
;                 bf16x8 kf[4];
; #pragma unroll
;                 for (int j4 = 0; j4 < 4; ++j4) kf[j4] = *(const LAS bf16x8*)(Kb + kfo + (g0 + j4) * 32);
; #pragma unroll
;                 for (int j4 = 0; j4 < 4; ++j4) { const int d0 = g0 + j4;
;                     s[0] = MFMA32(kf[j4], qf[d0], s[0]);
; #pragma unroll
;                     for (int j = 0; j < PER; ++j) { const int r = d0 * PER + j; s[1][r] = ((r >> 3) ? fb3 : fb2) + sl2 * (float)(r & 7); }
;                 }
;                 __builtin_amdgcn_sched_barrier(0);
;             }
;             __builtin_amdgcn_s_setprio(0);
;             if (need) {
; #pragma unroll
;                 for (int r = 0; r < 16; ++r) s[0][r] = (16 * (r >> 3) + (r & 7) > thr_eff) ? ATT_NEG : s[0][r];
;             }
;             float mx = fmaxf(fmaxf(s[0][0], s[0][1]), s[0][2]);
; #pragma unroll
;             for (int r = 3; r < 15; r += 2) mx = fmaxf(fmaxf(mx, s[0][r]), s[0][r + 1]);
;             mx = fmaxf(mx, s[0][15]);
;             __builtin_amdgcn_sched_barrier(0);
;             __builtin_amdgcn_s_setprio(1);
; #pragma unroll
;             for (int g0 = 0; g0 < NQK; g0 += 4) {
;                 bf16x8 kf[4];
; #pragma unroll
;                 for (int j4 = 0; j4 < 4; ++j4) kf[j4] = *(const LAS bf16x8*)(Kb + kfo + 32 * KP + (g0 + j4) * 32);
; #pragma unroll
;                 for (int j4 = 0; j4 < 4; ++j4) { const int d0 = g0 + j4;
;                     s[1] = MFMA32(kf[j4], qf[d0], s[1]);
; #pragma unroll
;                     for (int j = 0; j < PER; ++j) { const int r = d0 * PER + j; s[0][r] = __builtin_amdgcn_exp2f(s[0][r]); asm volatile("" : "+v"(s[0][r])); }
;                     __builtin_amdgcn_sched_barrier(0);
;                 }
;             }
.LBB0_676:
	v_or_b32_e32 v14, s66, v154
	v_sub_u32_e32 v15, v14, v189
	v_cvt_f32_i32_e32 v15, v15
	v_sub_u32_e32 v84, v189, v14
	s_and_b32 s14, s49, 1
	v_fma_f32 v14, v161, v15, -v1
	v_cndmask_b32_e64 v15, v216, v217, s[0:1]
	v_add_f32_e32 v80, v197, v14
	v_pk_add_f32 v[96:97], v[160:161], v[14:15] op_sel_hi:[1,0]
	v_pk_add_f32 v[98:99], v[168:169], v[14:15] op_sel_hi:[1,0]
	v_pk_add_f32 v[100:101], v[170:171], v[14:15] op_sel_hi:[1,0]
	v_pk_add_f32 v[102:103], v[172:173], v[14:15] op_sel_hi:[1,0]
	v_pk_add_f32 v[104:105], v[160:161], v[80:81] op_sel_hi:[1,0]
	v_pk_add_f32 v[106:107], v[168:169], v[80:81] op_sel_hi:[1,0]
	v_pk_add_f32 v[108:109], v[170:171], v[80:81] op_sel_hi:[1,0]
	v_pk_add_f32 v[110:111], v[172:173], v[80:81] op_sel_hi:[1,0]
	s_setprio 1
	s_mul_i32 s0, s14, 0x4400
	v_add_u32_e32 v180, s0, v198
	ds_read_b128 v[80:83], v180
	ds_read_b128 v[234:237], v180 offset:32
	ds_read_b128 v[238:241], v180 offset:64
	ds_read_b128 v[242:245], v180 offset:96
	s_mul_i32 s1, s14, 0x4800
	v_add_u32_e32 v250, s1, v201
	s_waitcnt vmcnt(4) lgkmcnt(3)
	v_mfma_f32_32x32x16_bf16 v[96:111], v[80:83], v[112:115], v[96:111]
	ds_read_b128 v[80:83], v180 offset:128
	s_waitcnt lgkmcnt(3)
	v_mfma_f32_32x32x16_bf16 v[96:111], v[234:237], v[116:119], v[96:111]
	ds_read_b128 v[234:237], v180 offset:160
	s_waitcnt lgkmcnt(3)
	v_mfma_f32_32x32x16_bf16 v[96:111], v[238:241], v[120:123], v[96:111]
	ds_read_b128 v[238:241], v180 offset:192
	s_waitcnt lgkmcnt(3)
	v_mfma_f32_32x32x16_bf16 v[96:111], v[242:245], v[124:127], v[96:111]
	ds_read_b128 v[242:245], v180 offset:224
	ds_read_b128 v[174:177], v180 offset:8704
	ds_read_b128 v[182:185], v180 offset:8736
	ds_read_b128 v[204:207], v180 offset:8768
	ds_read_b128 v[226:229], v180 offset:8800
	s_waitcnt lgkmcnt(7)
	v_mfma_f32_32x32x16_bf16 v[96:111], v[80:83], v[128:131], v[96:111]
	s_waitcnt lgkmcnt(6)
	v_mfma_f32_32x32x16_bf16 v[96:111], v[234:237], v[132:135], v[96:111]
	s_waitcnt lgkmcnt(5)
	v_mfma_f32_32x32x16_bf16 v[96:111], v[238:241], v[136:139], v[96:111]
	s_waitcnt lgkmcnt(4)
	v_mfma_f32_32x32x16_bf16 v[96:111], v[242:245], v[140:143], v[96:111]
	ds_read_b128 v[234:237], v250 offset:34816
	ds_read_b128 v[238:241], v250 offset:39424
	ds_read_b128 v[242:245], v250 offset:44032
	ds_read_b128 v[246:249], v250 offset:48640
	v_cndmask_b32_e64 v203, v15, v84, s[6:7]
	s_setprio 0
	v_cndmask_b32_e64 v15, 0, 1, s[12:13]
	v_cmp_ne_u32_e64 s[6:7], 1, v15
	s_andn2_b64 vcc, exec, s[12:13]
	s_cbranch_vccnz .LBB0_678
	v_cmp_lt_i32_e32 vcc, -1, v203
	s_nop 4
	v_cndmask_b32_e32 v96, v218, v96, vcc
	v_cmp_lt_i32_e32 vcc, 0, v203
	s_nop 1
	v_cndmask_b32_e32 v97, v218, v97, vcc
	v_cmp_lt_i32_e32 vcc, 1, v203
	s_nop 1
	v_cndmask_b32_e32 v98, v218, v98, vcc
	v_cmp_lt_i32_e32 vcc, 2, v203
	s_nop 1
	v_cndmask_b32_e32 v99, v218, v99, vcc
	v_cmp_lt_i32_e32 vcc, 3, v203
	s_nop 1
	v_cndmask_b32_e32 v100, v218, v100, vcc
	v_cmp_lt_i32_e32 vcc, 4, v203
	s_nop 1
	v_cndmask_b32_e32 v101, v218, v101, vcc
	v_cmp_lt_i32_e32 vcc, 5, v203
	s_nop 1
	v_cndmask_b32_e32 v102, v218, v102, vcc
	v_cmp_lt_i32_e32 vcc, 6, v203
	s_nop 1
	v_cndmask_b32_e32 v103, v218, v103, vcc
	v_cmp_lt_i32_e32 vcc, 15, v203
	s_nop 1
	v_cndmask_b32_e32 v104, v218, v104, vcc
	v_cmp_lt_i32_e32 vcc, 16, v203
	s_nop 1
	v_cndmask_b32_e32 v105, v218, v105, vcc
	v_cmp_lt_i32_e32 vcc, 17, v203
	s_nop 1
	v_cndmask_b32_e32 v106, v218, v106, vcc
	v_cmp_lt_i32_e32 vcc, 18, v203
	s_nop 1
	v_cndmask_b32_e32 v107, v218, v107, vcc
	v_cmp_lt_i32_e32 vcc, 19, v203
	s_nop 1
	v_cndmask_b32_e32 v108, v218, v108, vcc
	v_cmp_lt_i32_e32 vcc, 20, v203
	s_nop 1
	v_cndmask_b32_e32 v109, v218, v109, vcc
	v_cmp_lt_i32_e32 vcc, 21, v203
	s_nop 1
	v_cndmask_b32_e32 v110, v218, v110, vcc
	v_cmp_lt_i32_e32 vcc, 22, v203
	s_nop 1
	v_cndmask_b32_e32 v111, v218, v111, vcc
.LBB0_678:
	v_add_f32_e32 v86, v199, v14
	v_add_f32_e32 v14, v200, v14
	v_pk_add_f32 v[80:81], v[160:161], v[86:87] op_sel_hi:[1,0]
	v_pk_add_f32 v[82:83], v[168:169], v[86:87] op_sel_hi:[1,0]
	v_pk_add_f32 v[84:85], v[170:171], v[86:87] op_sel_hi:[1,0]
	v_pk_add_f32 v[86:87], v[172:173], v[86:87] op_sel_hi:[1,0]
	v_pk_add_f32 v[88:89], v[160:161], v[14:15] op_sel_hi:[1,0]
	v_pk_add_f32 v[90:91], v[168:169], v[14:15] op_sel_hi:[1,0]
	v_pk_add_f32 v[92:93], v[170:171], v[14:15] op_sel_hi:[1,0]
	v_pk_add_f32 v[94:95], v[172:173], v[14:15] op_sel_hi:[1,0]
	s_setprio 1
	v_exp_f32_e32 v14, v96
	v_exp_f32_e32 v15, v97
	s_waitcnt lgkmcnt(7)
	v_mfma_f32_32x32x16_bf16 v[80:95], v[174:177], v[112:115], v[80:95]
	s_waitcnt lgkmcnt(6)
	v_mfma_f32_32x32x16_bf16 v[80:95], v[182:185], v[116:119], v[80:95]
	v_exp_f32_e32 v174, v98
	v_exp_f32_e32 v175, v99
	s_waitcnt lgkmcnt(5)
	v_mfma_f32_32x32x16_bf16 v[80:95], v[204:207], v[120:123], v[80:95]
	v_exp_f32_e32 v176, v100
	v_exp_f32_e32 v177, v101
	s_waitcnt lgkmcnt(4)
	v_mfma_f32_32x32x16_bf16 v[80:95], v[226:229], v[124:127], v[80:95]
	v_exp_f32_e32 v178, v102
	v_exp_f32_e32 v179, v103
	ds_read_b128 v[182:185], v180 offset:8832
	ds_read_b128 v[204:207], v180 offset:8864
	ds_read_b128 v[226:229], v180 offset:8896
	ds_read_b128 v[230:233], v180 offset:8928
	v_exp_f32_e32 v180, v104
	s_waitcnt lgkmcnt(3)
	v_mfma_f32_32x32x16_bf16 v[80:95], v[182:185], v[128:131], v[80:95]
	v_exp_f32_e32 v181, v105
	s_waitcnt lgkmcnt(2)
	v_mfma_f32_32x32x16_bf16 v[80:95], v[204:207], v[132:135], v[80:95]
	v_exp_f32_e32 v182, v106
	v_exp_f32_e32 v183, v107
	s_waitcnt lgkmcnt(1)
	v_mfma_f32_32x32x16_bf16 v[80:95], v[226:229], v[136:139], v[80:95]
	v_exp_f32_e32 v184, v108
	v_exp_f32_e32 v185, v109
	s_waitcnt lgkmcnt(0)
	v_mfma_f32_32x32x16_bf16 v[80:95], v[230:233], v[140:143], v[80:95]
	v_exp_f32_e32 v186, v110
	v_exp_f32_e32 v187, v111
	s_setprio 0
	s_and_b64 vcc, exec, s[6:7]
	s_cbranch_vccnz .LBB0_680
	v_cmp_lt_i32_e32 vcc, 31, v203
	s_nop 5
	v_cndmask_b32_e32 v80, v218, v80, vcc
	v_cmp_lt_i32_e32 vcc, 32, v203
	s_nop 1
	v_cndmask_b32_e32 v81, v218, v81, vcc
	v_cmp_lt_i32_e32 vcc, 33, v203
	s_nop 1
	v_cndmask_b32_e32 v82, v218, v82, vcc
	v_cmp_lt_i32_e32 vcc, 34, v203
	s_nop 1
	v_cndmask_b32_e32 v83, v218, v83, vcc
	v_cmp_lt_i32_e32 vcc, 35, v203
	s_nop 1
	v_cndmask_b32_e32 v84, v218, v84, vcc
	v_cmp_lt_i32_e32 vcc, 36, v203
	s_nop 1
	v_cndmask_b32_e32 v85, v218, v85, vcc
	v_cmp_lt_i32_e32 vcc, 37, v203
	s_nop 1
	v_cndmask_b32_e32 v86, v218, v86, vcc
	v_cmp_lt_i32_e32 vcc, 38, v203
	s_nop 1
	v_cndmask_b32_e32 v87, v218, v87, vcc
	v_cmp_lt_i32_e32 vcc, 47, v203
	s_nop 1
	v_cndmask_b32_e32 v88, v218, v88, vcc
	v_cmp_lt_i32_e32 vcc, 48, v203
	s_nop 1
	v_cndmask_b32_e32 v89, v218, v89, vcc
	v_cmp_lt_i32_e32 vcc, 49, v203
	s_nop 1
	v_cndmask_b32_e32 v90, v218, v90, vcc
	v_cmp_lt_i32_e32 vcc, 50, v203
	s_nop 1
	v_cndmask_b32_e32 v91, v218, v91, vcc
	v_cmp_lt_i32_e32 vcc, 51, v203
	s_nop 1
	v_cndmask_b32_e32 v92, v218, v92, vcc
	v_cmp_lt_i32_e32 vcc, 52, v203
	s_nop 1
	v_cndmask_b32_e32 v93, v218, v93, vcc
	v_cmp_lt_i32_e32 vcc, 53, v203
	s_nop 1
	v_cndmask_b32_e32 v94, v218, v94, vcc
	v_cmp_lt_i32_e32 vcc, 54, v203
	s_nop 1
	v_cndmask_b32_e32 v95, v218, v95, vcc

; #define LAS __attribute__((address_space(3)))
; #define MFMA32(a, b, c) __builtin_amdgcn_mfma_f32_32x32x16_bf16((a), (b), (c), 0, 0, 0)
; #define PACK8(S, B) __builtin_bit_cast(bf16x8, (u32x4){cvt_pk_bf16(S[B], S[B + 1]), cvt_pk_bf16(S[B + 2], S[B + 3]), cvt_pk_bf16(S[B + 4], S[B + 5]), cvt_pk_bf16(S[B + 6], S[B + 7])})
; template <int DH, bool MOBA>
; __device__ __forceinline__ void flash_pass(LAS unsigned char* lds, const bf16_t* qrow, const bf16_t* kbase, const bf16_t* vtbase, int q0, int qblk, float sl2, unsigned sel, f32x16 (&o)[4], int tid) {
;     ...
;             float lsum = 0.f;
; #pragma unroll
;             for (int r = 0; r < 16; ++r) lsum += s[0][r];
;             bf16x8 pb[4];
;             pb[0] = PACK8(s[0], 0); pb[1] = PACK8(s[0], 8);
;             __builtin_amdgcn_sched_barrier(0);
;             __builtin_amdgcn_s_setprio(1);
; #pragma unroll
;             for (int c = 0; c < 2; ++c) {
;                 bf16x8 vf[4];
; #pragma unroll
;                 for (int d = 0; d < 4; ++d) vf[d] = *(const LAS bf16x8*)(Vb + vfo + d * 32 * ATT_VP + c * 32);
; #pragma unroll
;                 for (int d = 0; d < 4; ++d) { o[d] = MFMA32(vf[d], pb[c], o[d]);
;                     s[1][(c * 4 + d) * 2] = __builtin_amdgcn_exp2f(s[1][(c * 4 + d) * 2]); s[1][(c * 4 + d) * 2 + 1] = __builtin_amdgcn_exp2f(s[1][(c * 4 + d) * 2 + 1]);
;                     __builtin_amdgcn_sched_barrier(0); }
;             }
;             pb[2] = PACK8(s[1], 0); pb[3] = PACK8(s[1], 8);
;             __builtin_amdgcn_sched_barrier(0);
; #pragma unroll
;             for (int c = 2; c < 4; ++c) {
;                 bf16x8 vf[4];
; #pragma unroll
;                 for (int d = 0; d < 4; ++d) vf[d] = *(const LAS bf16x8*)(Vb + vfo + d * 32 * ATT_VP + c * 32);
; #pragma unroll
;                 for (int d = 0; d < 4; ++d) { o[d] = MFMA32(vf[d], pb[c], o[d]);
;                     lsum += s[1][((c - 2) * 4 + d) * 2] + s[1][((c - 2) * 4 + d) * 2 + 1];
;                     __builtin_amdgcn_sched_barrier(0); }
;             }
;             __builtin_amdgcn_s_setprio(0);
;             l_run += lsum;
.LBB0_682:
	s_mulk_i32 s14, 0x4800
	v_cvt_pk_bf16_f32 v96, v14, v15
	v_cvt_pk_bf16_f32 v97, v174, v175
	v_cvt_pk_bf16_f32 v98, v176, v177
	v_cvt_pk_bf16_f32 v99, v178, v179
	v_cvt_pk_bf16_f32 v100, v180, v181
	v_cvt_pk_bf16_f32 v101, v182, v183
	v_cvt_pk_bf16_f32 v102, v184, v185
	v_cvt_pk_bf16_f32 v103, v186, v187
	s_setprio 1
	v_add_u32_e32 v203, s14, v201
	v_exp_f32_e32 v209, v80
	s_waitcnt lgkmcnt(3)
	v_mfma_f32_32x32x16_bf16 v[64:79], v[234:237], v[96:99], v[64:79]
	v_exp_f32_e32 v231, v81
	s_waitcnt lgkmcnt(2)
	v_mfma_f32_32x32x16_bf16 v[48:63], v[238:241], v[96:99], v[48:63]
	v_exp_f32_e32 v208, v82
	v_exp_f32_e32 v230, v83
	s_waitcnt lgkmcnt(1)
	v_mfma_f32_32x32x16_bf16 v[32:47], v[242:245], v[96:99], v[32:47]
	v_exp_f32_e32 v109, v84
	v_exp_f32_e32 v111, v85
	s_waitcnt lgkmcnt(0)
	v_mfma_f32_32x32x16_bf16 v[16:31], v[246:249], v[96:99], v[16:31]
	v_exp_f32_e32 v108, v86
	v_exp_f32_e32 v110, v87
	ds_read_b128 v[80:83], v203 offset:34848
	ds_read_b128 v[84:87], v203 offset:39456
	ds_read_b128 v[96:99], v203 offset:44064
	ds_read_b128 v[104:107], v203 offset:48672
	ds_read_b128 v[234:237], v203 offset:34880
	ds_read_b128 v[238:241], v203 offset:39488
	ds_read_b128 v[242:245], v203 offset:44096
	ds_read_b128 v[246:249], v203 offset:48704
	v_exp_f32_e32 v205, v88
	s_waitcnt lgkmcnt(7)
	v_mfma_f32_32x32x16_bf16 v[64:79], v[80:83], v[100:103], v[64:79]
	v_exp_f32_e32 v207, v89
	s_waitcnt lgkmcnt(6)
	v_mfma_f32_32x32x16_bf16 v[48:63], v[84:87], v[100:103], v[48:63]
	v_exp_f32_e32 v204, v90
	v_exp_f32_e32 v206, v91
	s_waitcnt lgkmcnt(5)
	v_mfma_f32_32x32x16_bf16 v[32:47], v[96:99], v[100:103], v[32:47]
	v_exp_f32_e32 v227, v92
	v_exp_f32_e32 v229, v93
	s_waitcnt lgkmcnt(4)
	v_mfma_f32_32x32x16_bf16 v[16:31], v[104:107], v[100:103], v[16:31]
	v_exp_f32_e32 v226, v94
	v_exp_f32_e32 v228, v95
	v_add_f32_e32 v14, 0, v14
	v_add_f32_e32 v14, v15, v14
	v_add_f32_e32 v14, v174, v14
	v_add_f32_e32 v14, v175, v14
	v_add_f32_e32 v14, v176, v14
	v_add_f32_e32 v14, v177, v14
	v_add_f32_e32 v14, v178, v14
	v_add_f32_e32 v14, v179, v14
	v_add_f32_e32 v14, v180, v14
	v_add_f32_e32 v14, v181, v14
	v_add_f32_e32 v14, v182, v14
	v_add_f32_e32 v14, v183, v14
	v_add_f32_e32 v14, v184, v14
	v_add_f32_e32 v14, v185, v14
	v_add_f32_e32 v14, v186, v14
	v_add_f32_e32 v98, v187, v14
	ds_read_b128 v[80:83], v203 offset:34912
	ds_read_b128 v[84:87], v203 offset:39520
	ds_read_b128 v[88:91], v203 offset:44128
	ds_read_b128 v[92:95], v203 offset:48736
	v_pk_add_f32 v[14:15], v[208:209], v[230:231]
	v_cvt_pk_bf16_f32 v96, v209, v231
	v_add_f32_e32 v15, v15, v98
	v_cvt_pk_bf16_f32 v97, v208, v230
	v_add_f32_e32 v100, v14, v15
	v_cvt_pk_bf16_f32 v98, v109, v111
	v_cvt_pk_bf16_f32 v99, v108, v110
	v_pk_add_f32 v[14:15], v[108:109], v[110:111]
	s_waitcnt lgkmcnt(7)
	v_mfma_f32_32x32x16_bf16 v[64:79], v[234:237], v[96:99], v[64:79]
	v_add_f32_e32 v15, v15, v100
	v_add_f32_e32 v100, v14, v15
	s_waitcnt lgkmcnt(6)
	v_mfma_f32_32x32x16_bf16 v[48:63], v[238:241], v[96:99], v[48:63]
	s_waitcnt lgkmcnt(5)
	v_mfma_f32_32x32x16_bf16 v[32:47], v[242:245], v[96:99], v[32:47]
	s_waitcnt lgkmcnt(4)
	v_mfma_f32_32x32x16_bf16 v[16:31], v[246:249], v[96:99], v[16:31]
	v_add_f32_e64 v14, v204, v206
	v_add_f32_e64 v15, v205, v207
	v_cvt_pk_bf16_f32 v96, v205, v207
	v_add_f32_e32 v15, v15, v100
	v_cvt_pk_bf16_f32 v97, v204, v206
	v_add_f32_e32 v100, v14, v15
	v_cvt_pk_bf16_f32 v98, v227, v229
	v_cvt_pk_bf16_f32 v99, v226, v228
	v_pk_add_f32 v[14:15], v[226:227], v[228:229]
	s_waitcnt lgkmcnt(3)
	v_mfma_f32_32x32x16_bf16 v[64:79], v[80:83], v[96:99], v[64:79]
	v_add_f32_e32 v15, v15, v100
	v_add_f32_e32 v14, v14, v15
	s_waitcnt lgkmcnt(2)
	v_mfma_f32_32x32x16_bf16 v[48:63], v[84:87], v[96:99], v[48:63]
	s_waitcnt lgkmcnt(1)
	v_mfma_f32_32x32x16_bf16 v[32:47], v[88:91], v[96:99], v[32:47]
	s_waitcnt lgkmcnt(0)
	v_mfma_f32_32x32x16_bf16 v[16:31], v[92:95], v[96:99], v[16:31]
	s_setprio 0
	v_add_f32_e32 v202, v202, v14

; template <int DH, bool MOBA>
; __device__ __forceinline__ void flash_pass(LAS unsigned char* lds, const bf16_t* qrow, const bf16_t* kbase, const bf16_t* vtbase, int q0, int qblk, float sl2, unsigned sel, f32x16 (&o)[4], int tid) {
;     ...
;             f32x16 s[2];
;             const float fb = sl2 * (float)(kv0 + 8 * hi - qpos) - m_run;
;             const int thr = qpos - kv0 - 8 * hi;
;             const bool need = (diag && kv0 + 63 > qw0) || (MOBA && !diag && !__all(mysel ? 1 : 0));
;             int thr_eff = diag ? thr : 4096;
;             if (MOBA) thr_eff = (!diag && !mysel) ? -4096 : thr_eff;
;             constexpr int NQK = DH / 16, PER = 16 / NQK;
;             {
;                 const float fb0 = fb, fb1 = fb + sl2 * 16.0f;
; #pragma unroll
;                 for (int r = 0; r < 16; ++r) s[0][r] = ((r >> 3) ? fb1 : fb0) + sl2 * (float)(r & 7);
;             }
;             const float fb2 = fb + sl2 * 32.0f, fb3 = fb + sl2 * 48.0f;
;             __builtin_amdgcn_s_setprio(1);
; #pragma unroll
;             for (int g0 = 0; g0 < NQK; g0 += 4) {
;                 bf16x8 kf[4];
; #pragma unroll
;                 for (int j4 = 0; j4 < 4; ++j4) kf[j4] = *(const LAS bf16x8*)(Kb + kfo + (g0 + j4) * 32);
; #pragma unroll
;                 for (int j4 = 0; j4 < 4; ++j4) { const int d0 = g0 + j4;
;                     s[0] = MFMA32(kf[j4], qf[d0], s[0]);
; #pragma unroll
;                     for (int j = 0; j < PER; ++j) { const int r = d0 * PER + j; s[1][r] = ((r >> 3) ? fb3 : fb2) + sl2 * (float)(r & 7); }
;                 }
;                 __builtin_amdgcn_sched_barrier(0);
;             }
;             __builtin_amdgcn_s_setprio(0);
;             if (need) {
; #pragma unroll
;                 for (int r = 0; r < 16; ++r) s[0][r] = (16 * (r >> 3) + (r & 7) > thr_eff) ? ATT_NEG : s[0][r];
;             }
;             float mx = fmaxf(fmaxf(s[0][0], s[0][1]), s[0][2]);
; #pragma unroll
;             for (int r = 3; r < 15; r += 2) mx = fmaxf(fmaxf(mx, s[0][r]), s[0][r + 1]);
;             mx = fmaxf(mx, s[0][15]);
;             __builtin_amdgcn_sched_barrier(0);
;             __builtin_amdgcn_s_setprio(1);
; #pragma unroll
;             for (int g0 = 0; g0 < NQK; g0 += 4) {
;                 bf16x8 kf[4];
; #pragma unroll
;                 for (int j4 = 0; j4 < 4; ++j4) kf[j4] = *(const LAS bf16x8*)(Kb + kfo + 32 * KP + (g0 + j4) * 32);
.LBB0_690:
	s_lshr_b32 s6, s12, 2
	s_add_i32 s85, s12, 1
	s_cmp_lt_u32 s85, s46
	s_cselect_b32 s7, s85, s12
	s_lshl_b32 s10, s7, 6
	v_add_u32_e32 v66, s10, v136
	v_ashrrev_i32_e32 v67, 31, v66
	v_lshlrev_b64 v[66:67], 14, v[66:67]
	v_lshl_add_u64 v[66:67], v[164:165], 0, v[66:67]
	v_lshl_add_u64 v[68:69], s[10:11], 1, v[140:141]
	v_lshl_add_u64 v[70:71], v[68:69], 0, v[142:143]
	global_load_dwordx4 v[122:125], v[66:67], off offset:2048
	global_load_dwordx4 v[114:117], v[70:71], off
	v_lshl_add_u64 v[66:67], v[68:69], 0, v[146:147]
	global_load_dwordx4 v[118:121], v[66:67], off
	s_cmp_lg_u32 s6, s83
	s_cselect_b64 s[6:7], -1, 0
	s_cmp_le_i32 s49, s48
	s_cselect_b64 s[66:67], -1, 0
	s_or_b64 s[66:67], s[6:7], s[66:67]
	s_andn2_b64 vcc, exec, s[66:67]
	s_cbranch_vccnz .LBB0_698
	v_add_u32_e32 v66, s49, v190
	v_cvt_f32_i32_e32 v66, v66
	s_and_b32 s10, s12, 1
	s_add_i32 s12, s49, 63
	s_cmp_le_i32 s12, s47
	v_fma_f32 v74, v155, v66, -v1
	s_cselect_b64 s[12:13], -1, 0
	v_add_f32_e32 v66, v182, v74
	s_or_b64 s[12:13], s[6:7], s[12:13]
	v_pk_add_f32 v[82:83], v[154:155], v[74:75] op_sel_hi:[1,0]
	v_pk_add_f32 v[84:85], v[156:157], v[74:75] op_sel_hi:[1,0]
	v_pk_add_f32 v[86:87], v[158:159], v[74:75] op_sel_hi:[1,0]
	v_pk_add_f32 v[88:89], v[160:161], v[74:75] op_sel_hi:[1,0]
	v_pk_add_f32 v[90:91], v[154:155], v[66:67] op_sel_hi:[1,0]
	v_pk_add_f32 v[92:93], v[156:157], v[66:67] op_sel_hi:[1,0]
	v_pk_add_f32 v[94:95], v[158:159], v[66:67] op_sel_hi:[1,0]
	v_pk_add_f32 v[96:97], v[160:161], v[66:67] op_sel_hi:[1,0]
	s_setprio 1
	s_mul_i32 s66, s10, 0x4400
	v_add_u32_e32 v166, s66, v183
	ds_read_b128 v[66:69], v166
	ds_read_b128 v[234:237], v166 offset:32
	ds_read_b128 v[238:241], v166 offset:64
	ds_read_b128 v[242:245], v166 offset:96
	ds_read_b128 v[170:173], v166 offset:4608
	ds_read_b128 v[174:177], v166 offset:4640
	ds_read_b128 v[178:181], v166 offset:4672
	ds_read_b128 v[194:197], v166 offset:4704
	s_mul_i32 s66, s10, 0x4800
	v_add_u32_e32 v250, s66, v186
	v_cndmask_b32_e64 v192, v189, v217, s[6:7]
	s_waitcnt lgkmcnt(7)
	v_mfma_f32_32x32x16_bf16 v[82:97], v[66:69], v[98:101], v[82:97]
	s_waitcnt lgkmcnt(6)
	v_mfma_f32_32x32x16_bf16 v[82:97], v[234:237], v[102:105], v[82:97]
	s_waitcnt lgkmcnt(5)
	v_mfma_f32_32x32x16_bf16 v[82:97], v[238:241], v[106:109], v[82:97]
	s_waitcnt lgkmcnt(4)
	v_mfma_f32_32x32x16_bf16 v[82:97], v[242:245], v[110:113], v[82:97]
	ds_read_b128 v[234:237], v250 offset:34816
	ds_read_b128 v[238:241], v250 offset:39424
	ds_read_b128 v[242:245], v250 offset:44032
	ds_read_b128 v[246:249], v250 offset:48640
	s_setprio 0
	s_and_b64 vcc, exec, s[12:13]
	s_cbranch_vccnz .LBB0_693
	v_cmp_lt_i32_e32 vcc, -1, v192
	s_nop 7
	v_cndmask_b32_e32 v82, v218, v82, vcc
	v_cmp_lt_i32_e32 vcc, 0, v192
	s_nop 1
	v_cndmask_b32_e32 v83, v218, v83, vcc
	v_cmp_lt_i32_e32 vcc, 1, v192
	s_nop 1
	v_cndmask_b32_e32 v84, v218, v84, vcc
	v_cmp_lt_i32_e32 vcc, 2, v192
	s_nop 1
	v_cndmask_b32_e32 v85, v218, v85, vcc
	v_cmp_lt_i32_e32 vcc, 3, v192
	s_nop 1
	v_cndmask_b32_e32 v86, v218, v86, vcc
	v_cmp_lt_i32_e32 vcc, 4, v192
	s_nop 1
	v_cndmask_b32_e32 v87, v218, v87, vcc
	v_cmp_lt_i32_e32 vcc, 5, v192
	s_nop 1
	v_cndmask_b32_e32 v88, v218, v88, vcc
	v_cmp_lt_i32_e32 vcc, 6, v192
	s_nop 1
	v_cndmask_b32_e32 v89, v218, v89, vcc
	v_cmp_lt_i32_e32 vcc, 15, v192
	s_nop 1
	v_cndmask_b32_e32 v90, v218, v90, vcc
	v_cmp_lt_i32_e32 vcc, 16, v192
	s_nop 1
	v_cndmask_b32_e32 v91, v218, v91, vcc
	v_cmp_lt_i32_e32 vcc, 17, v192
	s_nop 1
	v_cndmask_b32_e32 v92, v218, v92, vcc
	v_cmp_lt_i32_e32 vcc, 18, v192
	s_nop 1
	v_cndmask_b32_e32 v93, v218, v93, vcc
	v_cmp_lt_i32_e32 vcc, 19, v192
	s_nop 1
	v_cndmask_b32_e32 v94, v218, v94, vcc
	v_cmp_lt_i32_e32 vcc, 20, v192
	s_nop 1
	v_cndmask_b32_e32 v95, v218, v95, vcc
	v_cmp_lt_i32_e32 vcc, 21, v192
	s_nop 1
	v_cndmask_b32_e32 v96, v218, v96, vcc
	v_cmp_lt_i32_e32 vcc, 22, v192
	s_nop 1
	v_cndmask_b32_e32 v97, v218, v97, vcc
.LBB0_693:
	v_add_f32_e32 v72, v184, v74
	v_add_f32_e32 v80, v185, v74
	v_pk_add_f32 v[66:67], v[154:155], v[72:73] op_sel_hi:[1,0]
	v_pk_add_f32 v[68:69], v[156:157], v[72:73] op_sel_hi:[1,0]
	v_pk_add_f32 v[70:71], v[158:159], v[72:73] op_sel_hi:[1,0]
	v_pk_add_f32 v[72:73], v[160:161], v[72:73] op_sel_hi:[1,0]
	v_pk_add_f32 v[74:75], v[154:155], v[80:81] op_sel_hi:[1,0]
	v_pk_add_f32 v[76:77], v[156:157], v[80:81] op_sel_hi:[1,0]
	v_pk_add_f32 v[78:79], v[158:159], v[80:81] op_sel_hi:[1,0]
	v_pk_add_f32 v[80:81], v[160:161], v[80:81] op_sel_hi:[1,0]
	s_xor_b64 s[6:7], s[12:13], -1
	s_setprio 1
	v_exp_f32_e32 v166, v82
	s_waitcnt lgkmcnt(7)
	v_mfma_f32_32x32x16_bf16 v[66:81], v[170:173], v[98:101], v[66:81]
	v_exp_f32_e32 v167, v83
	v_exp_f32_e32 v168, v84
	v_exp_f32_e32 v169, v85
	s_waitcnt lgkmcnt(6)
	v_mfma_f32_32x32x16_bf16 v[66:81], v[174:177], v[102:105], v[66:81]
	v_exp_f32_e32 v170, v86
	v_exp_f32_e32 v171, v87
	v_exp_f32_e32 v172, v88
	v_exp_f32_e32 v173, v89
	s_waitcnt lgkmcnt(5)
	v_mfma_f32_32x32x16_bf16 v[66:81], v[178:181], v[106:109], v[66:81]
	v_exp_f32_e32 v174, v90
	v_exp_f32_e32 v175, v91
	v_exp_f32_e32 v176, v92
	v_exp_f32_e32 v177, v93
	s_waitcnt lgkmcnt(4)
	v_mfma_f32_32x32x16_bf16 v[66:81], v[194:197], v[110:113], v[66:81]
	v_exp_f32_e32 v178, v94
	v_exp_f32_e32 v179, v95
	v_exp_f32_e32 v180, v96
	v_exp_f32_e32 v181, v97
	s_setprio 0
	s_andn2_b64 vcc, exec, s[6:7]
	s_cbranch_vccnz .LBB0_695
	v_cmp_lt_i32_e32 vcc, 31, v192
	s_nop 3
	v_cndmask_b32_e32 v66, v218, v66, vcc
	v_cmp_lt_i32_e32 vcc, 32, v192
	s_nop 1
	v_cndmask_b32_e32 v67, v218, v67, vcc
	v_cmp_lt_i32_e32 vcc, 33, v192
	s_nop 1
	v_cndmask_b32_e32 v68, v218, v68, vcc
	v_cmp_lt_i32_e32 vcc, 34, v192
	s_nop 1
	v_cndmask_b32_e32 v69, v218, v69, vcc
	v_cmp_lt_i32_e32 vcc, 35, v192
	s_nop 1
	v_cndmask_b32_e32 v70, v218, v70, vcc
	v_cmp_lt_i32_e32 vcc, 36, v192
	s_nop 1
	v_cndmask_b32_e32 v71, v218, v71, vcc
	v_cmp_lt_i32_e32 vcc, 37, v192
	s_nop 1
	v_cndmask_b32_e32 v72, v218, v72, vcc
	v_cmp_lt_i32_e32 vcc, 38, v192
	s_nop 1
	v_cndmask_b32_e32 v73, v218, v73, vcc
	v_cmp_lt_i32_e32 vcc, 47, v192
	s_nop 1
	v_cndmask_b32_e32 v74, v218, v74, vcc
	v_cmp_lt_i32_e32 vcc, 48, v192
	s_nop 1
	v_cndmask_b32_e32 v75, v218, v75, vcc
	v_cmp_lt_i32_e32 vcc, 49, v192
	s_nop 1
	v_cndmask_b32_e32 v76, v218, v76, vcc
	v_cmp_lt_i32_e32 vcc, 50, v192
	s_nop 1
	v_cndmask_b32_e32 v77, v218, v77, vcc
	v_cmp_lt_i32_e32 vcc, 51, v192
	s_nop 1
	v_cndmask_b32_e32 v78, v218, v78, vcc
	v_cmp_lt_i32_e32 vcc, 52, v192
	s_nop 1
	v_cndmask_b32_e32 v79, v218, v79, vcc
	v_cmp_lt_i32_e32 vcc, 53, v192
	s_nop 1
	v_cndmask_b32_e32 v80, v218, v80, vcc
	v_cmp_lt_i32_e32 vcc, 54, v192
	s_nop 1
	v_cndmask_b32_e32 v81, v218, v81, vcc

; #define LAS __attribute__((address_space(3)))
; #define MFMA32(a, b, c) __builtin_amdgcn_mfma_f32_32x32x16_bf16((a), (b), (c), 0, 0, 0)
; #define PACK8(S, B) __builtin_bit_cast(bf16x8, (u32x4){cvt_pk_bf16(S[B], S[B + 1]), cvt_pk_bf16(S[B + 2], S[B + 3]), cvt_pk_bf16(S[B + 4], S[B + 5]), cvt_pk_bf16(S[B + 6], S[B + 7])})
; template <int DH, bool MOBA>
; __device__ __forceinline__ void flash_pass(LAS unsigned char* lds, const bf16_t* qrow, const bf16_t* kbase, const bf16_t* vtbase, int q0, int qblk, float sl2, unsigned sel, f32x16 (&o)[4], int tid) {
;     ...
;             float lsum = 0.f;
; #pragma unroll
;             for (int r = 0; r < 16; ++r) lsum += s[0][r];
;             bf16x8 pb[4];
;             pb[0] = PACK8(s[0], 0); pb[1] = PACK8(s[0], 8);
;             __builtin_amdgcn_sched_barrier(0);
;             __builtin_amdgcn_s_setprio(1);
; #pragma unroll
;             for (int c = 0; c < 2; ++c) {
;                 bf16x8 vf[4];
; #pragma unroll
;                 for (int d = 0; d < 4; ++d) vf[d] = *(const LAS bf16x8*)(Vb + vfo + d * 32 * ATT_VP + c * 32);
; #pragma unroll
;                 for (int d = 0; d < 4; ++d) { o[d] = MFMA32(vf[d], pb[c], o[d]);
;                     s[1][(c * 4 + d) * 2] = __builtin_amdgcn_exp2f(s[1][(c * 4 + d) * 2]); s[1][(c * 4 + d) * 2 + 1] = __builtin_amdgcn_exp2f(s[1][(c * 4 + d) * 2 + 1]);
;                     __builtin_amdgcn_sched_barrier(0); }
;             }
;             pb[2] = PACK8(s[1], 0); pb[3] = PACK8(s[1], 8);
;             __builtin_amdgcn_sched_barrier(0);
; #pragma unroll
;             for (int c = 2; c < 4; ++c) {
;                 bf16x8 vf[4];
; #pragma unroll
;                 for (int d = 0; d < 4; ++d) vf[d] = *(const LAS bf16x8*)(Vb + vfo + d * 32 * ATT_VP + c * 32);
; #pragma unroll
;                 for (int d = 0; d < 4; ++d) { o[d] = MFMA32(vf[d], pb[c], o[d]);
;                     lsum += s[1][((c - 2) * 4 + d) * 2] + s[1][((c - 2) * 4 + d) * 2 + 1];
;                     __builtin_amdgcn_sched_barrier(0); }
;             }
;             __builtin_amdgcn_s_setprio(0);
;             l_run += lsum;
.LBB0_697:
	s_mulk_i32 s10, 0x4800
	v_cvt_pk_bf16_f32 v82, v166, v167
	v_cvt_pk_bf16_f32 v83, v168, v169
	v_cvt_pk_bf16_f32 v84, v170, v171
	v_cvt_pk_bf16_f32 v85, v172, v173
	v_cvt_pk_bf16_f32 v86, v174, v175
	v_cvt_pk_bf16_f32 v87, v176, v177
	v_cvt_pk_bf16_f32 v88, v178, v179
	v_cvt_pk_bf16_f32 v89, v180, v181
	s_setprio 1
	v_add_u32_e32 v204, s10, v186
	v_exp_f32_e32 v201, v66
	s_waitcnt lgkmcnt(3)
	v_mfma_f32_32x32x16_bf16 v[50:65], v[234:237], v[82:85], v[50:65]
	v_exp_f32_e32 v203, v67
	s_waitcnt lgkmcnt(2)
	v_mfma_f32_32x32x16_bf16 v[34:49], v[238:241], v[82:85], v[34:49]
	v_exp_f32_e32 v200, v68
	v_exp_f32_e32 v202, v69
	s_waitcnt lgkmcnt(1)
	v_mfma_f32_32x32x16_bf16 v[18:33], v[242:245], v[82:85], v[18:33]
	v_exp_f32_e32 v95, v70
	v_exp_f32_e32 v97, v71
	s_waitcnt lgkmcnt(0)
	v_mfma_f32_32x32x16_bf16 v[2:17], v[246:249], v[82:85], v[2:17]
	v_exp_f32_e32 v94, v72
	v_exp_f32_e32 v96, v73
	ds_read_b128 v[66:69], v204 offset:34848
	ds_read_b128 v[70:73], v204 offset:39456
	ds_read_b128 v[82:85], v204 offset:44064
	ds_read_b128 v[90:93], v204 offset:48672
	ds_read_b128 v[234:237], v204 offset:34880
	ds_read_b128 v[238:241], v204 offset:39488
	ds_read_b128 v[242:245], v204 offset:44096
	ds_read_b128 v[246:249], v204 offset:48704
	v_exp_f32_e32 v193, v74
	s_waitcnt lgkmcnt(7)
	v_mfma_f32_32x32x16_bf16 v[50:65], v[66:69], v[86:89], v[50:65]
	v_exp_f32_e32 v195, v75
	s_waitcnt lgkmcnt(6)
	v_mfma_f32_32x32x16_bf16 v[34:49], v[70:73], v[86:89], v[34:49]
	v_exp_f32_e32 v192, v76
	v_exp_f32_e32 v194, v77
	s_waitcnt lgkmcnt(5)
	v_mfma_f32_32x32x16_bf16 v[18:33], v[82:85], v[86:89], v[18:33]
	v_exp_f32_e32 v197, v78
	v_exp_f32_e32 v199, v79
	s_waitcnt lgkmcnt(4)
	v_mfma_f32_32x32x16_bf16 v[2:17], v[90:93], v[86:89], v[2:17]
	v_exp_f32_e32 v196, v80
	v_exp_f32_e32 v198, v81
	v_add_f32_e32 v66, 0, v166
	v_add_f32_e32 v66, v167, v66
	v_add_f32_e32 v66, v168, v66
	v_add_f32_e32 v66, v169, v66
	v_add_f32_e32 v66, v170, v66
	v_add_f32_e32 v66, v171, v66
	v_add_f32_e32 v66, v172, v66
	v_add_f32_e32 v66, v173, v66
	v_add_f32_e32 v66, v174, v66
	v_add_f32_e32 v66, v175, v66
	v_add_f32_e32 v66, v176, v66
	v_add_f32_e32 v66, v177, v66
	v_add_f32_e32 v66, v178, v66
	v_add_f32_e32 v66, v179, v66
	v_add_f32_e32 v66, v180, v66
	v_add_f32_e32 v86, v181, v66
	ds_read_b128 v[66:69], v204 offset:34912
	ds_read_b128 v[70:73], v204 offset:39520
	ds_read_b128 v[74:77], v204 offset:44128
	ds_read_b128 v[78:81], v204 offset:48736
	v_pk_add_f32 v[84:85], v[200:201], v[202:203]
	v_cvt_pk_bf16_f32 v82, v201, v203
	v_add_f32_e32 v85, v85, v86
	v_cvt_pk_bf16_f32 v83, v200, v202
	v_add_f32_e32 v86, v84, v85
	v_cvt_pk_bf16_f32 v84, v95, v97
	v_cvt_pk_bf16_f32 v85, v94, v96
	s_waitcnt lgkmcnt(7)
	s_nop 0
	v_mfma_f32_32x32x16_bf16 v[50:65], v[234:237], v[82:85], v[50:65]
	v_add_f32_e64 v250, v94, v96
	v_add_f32_e64 v251, v95, v97
	v_add_f32_e32 v251, v251, v86
	v_add_f32_e32 v86, v250, v251
	s_waitcnt lgkmcnt(6)
	v_mfma_f32_32x32x16_bf16 v[34:49], v[238:241], v[82:85], v[34:49]
	s_waitcnt lgkmcnt(5)
	v_mfma_f32_32x32x16_bf16 v[18:33], v[242:245], v[82:85], v[18:33]
	s_waitcnt lgkmcnt(4)
	v_mfma_f32_32x32x16_bf16 v[2:17], v[246:249], v[82:85], v[2:17]
	v_add_f32_e64 v84, v192, v194
	v_add_f32_e64 v85, v193, v195
	v_cvt_pk_bf16_f32 v82, v193, v195
	v_add_f32_e32 v85, v85, v86
	v_cvt_pk_bf16_f32 v83, v192, v194
	v_add_f32_e32 v86, v84, v85
	v_cvt_pk_bf16_f32 v84, v197, v199
	v_cvt_pk_bf16_f32 v85, v196, v198
	s_waitcnt lgkmcnt(3)
	s_nop 0
	v_mfma_f32_32x32x16_bf16 v[50:65], v[66:69], v[82:85], v[50:65]
	v_add_f32_e64 v66, v196, v198
	v_add_f32_e64 v67, v197, v199
	v_add_f32_e32 v67, v67, v86
	v_add_f32_e32 v66, v66, v67
	s_waitcnt lgkmcnt(2)
	v_mfma_f32_32x32x16_bf16 v[34:49], v[70:73], v[82:85], v[34:49]
	s_waitcnt lgkmcnt(1)
	v_mfma_f32_32x32x16_bf16 v[18:33], v[74:77], v[82:85], v[18:33]
	s_waitcnt lgkmcnt(0)
	v_mfma_f32_32x32x16_bf16 v[2:17], v[78:81], v[82:85], v[2:17]
	s_setprio 0
	v_add_f32_e32 v191, v191, v66
